# P4 second dv-half: the six Q row-group reloads of stage_q_scaled issued together with counted waits instead of one global round trip each
# speedup vs baseline: 1.0021x; 1.0021x over previous
.LBB0_739:
	ds_read_b32 v8, v196 offset:4
	s_xor_b64 s[20:21], s[30:31], -1
	s_and_b64 vcc, exec, s[20:21]
	s_mov_b64 s[30:31], -1
	s_cbranch_vccz .LBB0_741
	global_load_dwordx4 v[4:7], v[96:97], off
	global_load_dwordx4 v[240:243], v[98:99], off
	global_load_dwordx4 v[244:247], v[100:101], off
	global_load_dwordx4 v[248:251], v[102:103], off
	global_load_dwordx4 v[252:255], v[104:105], off
	global_load_dwordx4 v[20:23], v[106:107], off
	s_mov_b64 s[30:31], 0
	s_waitcnt vmcnt(5) lgkmcnt(0)
	v_lshlrev_b32_e32 v10, 16, v4
	v_and_b32_e32 v11, 0xffff0000, v4
	v_pk_mul_f32 v[10:11], v[8:9], v[10:11] op_sel_hi:[0,1]
	v_cvt_pk_bf16_f32 v4, v10, v11
	v_lshlrev_b32_e32 v10, 16, v5
	v_and_b32_e32 v11, 0xffff0000, v5
	v_pk_mul_f32 v[10:11], v[8:9], v[10:11] op_sel_hi:[0,1]
	v_cvt_pk_bf16_f32 v5, v10, v11
	v_lshlrev_b32_e32 v10, 16, v6
	v_and_b32_e32 v11, 0xffff0000, v6
	v_pk_mul_f32 v[10:11], v[8:9], v[10:11] op_sel_hi:[0,1]
	v_cvt_pk_bf16_f32 v6, v10, v11
	v_lshlrev_b32_e32 v10, 16, v7
	v_and_b32_e32 v11, 0xffff0000, v7
	v_pk_mul_f32 v[10:11], v[8:9], v[10:11] op_sel_hi:[0,1]
	v_cvt_pk_bf16_f32 v7, v10, v11
	ds_write_b128 v85, v[4:7]
	ds_read_b32 v10, v197 offset:4
	s_waitcnt vmcnt(4) lgkmcnt(0)
	v_lshlrev_b32_e32 v12, 16, v240
	v_and_b32_e32 v13, 0xffff0000, v240
	v_pk_mul_f32 v[12:13], v[10:11], v[12:13] op_sel_hi:[0,1]
	v_cvt_pk_bf16_f32 v240, v12, v13
	v_lshlrev_b32_e32 v12, 16, v241
	v_and_b32_e32 v13, 0xffff0000, v241
	v_pk_mul_f32 v[12:13], v[10:11], v[12:13] op_sel_hi:[0,1]
	v_cvt_pk_bf16_f32 v241, v12, v13
	v_lshlrev_b32_e32 v12, 16, v242
	v_and_b32_e32 v13, 0xffff0000, v242
	v_pk_mul_f32 v[12:13], v[10:11], v[12:13] op_sel_hi:[0,1]
	v_cvt_pk_bf16_f32 v242, v12, v13
	v_lshlrev_b32_e32 v12, 16, v243
	v_and_b32_e32 v13, 0xffff0000, v243
	v_pk_mul_f32 v[10:11], v[10:11], v[12:13] op_sel_hi:[0,1]
	v_cvt_pk_bf16_f32 v243, v10, v11
	ds_write_b128 v85, v[240:243] offset:4352
	ds_read_b32 v10, v198 offset:4
	s_waitcnt vmcnt(3) lgkmcnt(0)
	v_lshlrev_b32_e32 v12, 16, v244
	v_and_b32_e32 v13, 0xffff0000, v244
	v_pk_mul_f32 v[12:13], v[10:11], v[12:13] op_sel_hi:[0,1]
	v_cvt_pk_bf16_f32 v244, v12, v13
	v_lshlrev_b32_e32 v12, 16, v245
	v_and_b32_e32 v13, 0xffff0000, v245
	v_pk_mul_f32 v[12:13], v[10:11], v[12:13] op_sel_hi:[0,1]
	v_cvt_pk_bf16_f32 v245, v12, v13
	v_lshlrev_b32_e32 v12, 16, v246
	v_and_b32_e32 v13, 0xffff0000, v246
	v_pk_mul_f32 v[12:13], v[10:11], v[12:13] op_sel_hi:[0,1]
	v_cvt_pk_bf16_f32 v246, v12, v13
	v_lshlrev_b32_e32 v12, 16, v247
	v_and_b32_e32 v13, 0xffff0000, v247
	v_pk_mul_f32 v[10:11], v[10:11], v[12:13] op_sel_hi:[0,1]
	v_cvt_pk_bf16_f32 v247, v10, v11
	ds_write_b128 v85, v[244:247] offset:8704
	ds_read_b32 v10, v199 offset:4
	s_waitcnt vmcnt(2) lgkmcnt(0)
	v_lshlrev_b32_e32 v12, 16, v248
	v_and_b32_e32 v13, 0xffff0000, v248
	v_pk_mul_f32 v[12:13], v[10:11], v[12:13] op_sel_hi:[0,1]
	v_cvt_pk_bf16_f32 v248, v12, v13
	v_lshlrev_b32_e32 v12, 16, v249
	v_and_b32_e32 v13, 0xffff0000, v249
	v_pk_mul_f32 v[12:13], v[10:11], v[12:13] op_sel_hi:[0,1]
	v_cvt_pk_bf16_f32 v249, v12, v13
	v_lshlrev_b32_e32 v12, 16, v250
	v_and_b32_e32 v13, 0xffff0000, v250
	v_pk_mul_f32 v[12:13], v[10:11], v[12:13] op_sel_hi:[0,1]
	v_cvt_pk_bf16_f32 v250, v12, v13
	v_lshlrev_b32_e32 v12, 16, v251
	v_and_b32_e32 v13, 0xffff0000, v251
	v_pk_mul_f32 v[10:11], v[10:11], v[12:13] op_sel_hi:[0,1]
	v_cvt_pk_bf16_f32 v251, v10, v11
	ds_write_b128 v85, v[248:251] offset:13056
	ds_read_b32 v10, v200 offset:4
	s_waitcnt vmcnt(1) lgkmcnt(0)
	v_lshlrev_b32_e32 v12, 16, v252
	v_and_b32_e32 v13, 0xffff0000, v252
	v_pk_mul_f32 v[12:13], v[10:11], v[12:13] op_sel_hi:[0,1]
	v_cvt_pk_bf16_f32 v252, v12, v13
	v_lshlrev_b32_e32 v12, 16, v253
	v_and_b32_e32 v13, 0xffff0000, v253
	v_pk_mul_f32 v[12:13], v[10:11], v[12:13] op_sel_hi:[0,1]
	v_cvt_pk_bf16_f32 v253, v12, v13
	v_lshlrev_b32_e32 v12, 16, v254
	v_and_b32_e32 v13, 0xffff0000, v254
	v_pk_mul_f32 v[12:13], v[10:11], v[12:13] op_sel_hi:[0,1]
	v_cvt_pk_bf16_f32 v254, v12, v13
	v_lshlrev_b32_e32 v12, 16, v255
	v_and_b32_e32 v13, 0xffff0000, v255
	v_pk_mul_f32 v[10:11], v[10:11], v[12:13] op_sel_hi:[0,1]
	v_cvt_pk_bf16_f32 v255, v10, v11
	ds_write_b128 v85, v[252:255] offset:17408
	ds_read_b32 v10, v201 offset:4
	s_waitcnt vmcnt(0) lgkmcnt(0)
	v_lshlrev_b32_e32 v12, 16, v20
	v_and_b32_e32 v13, 0xffff0000, v20
	v_pk_mul_f32 v[12:13], v[10:11], v[12:13] op_sel_hi:[0,1]
	v_cvt_pk_bf16_f32 v20, v12, v13
	v_lshlrev_b32_e32 v12, 16, v21
	v_and_b32_e32 v13, 0xffff0000, v21
	v_pk_mul_f32 v[12:13], v[10:11], v[12:13] op_sel_hi:[0,1]
	v_cvt_pk_bf16_f32 v21, v12, v13
	v_lshlrev_b32_e32 v12, 16, v22
	v_and_b32_e32 v13, 0xffff0000, v22
	v_pk_mul_f32 v[12:13], v[10:11], v[12:13] op_sel_hi:[0,1]
	v_cvt_pk_bf16_f32 v22, v12, v13
	v_lshlrev_b32_e32 v12, 16, v23
	v_and_b32_e32 v13, 0xffff0000, v23
	v_pk_mul_f32 v[10:11], v[10:11], v[12:13] op_sel_hi:[0,1]
	v_cvt_pk_bf16_f32 v23, v10, v11
	ds_write_b128 v85, v[20:23] offset:21760
	global_load_dwordx4 v[4:7], v[108:109], off
